# v18: attention K and V via LDS-DMA with SGPR-base + 32-bit lane offsets (no 64-bit address VALU)
# speedup vs baseline: 1.0425x; 1.0425x over previous
; __device__ __forceinline__ unsigned cvtpk(float lo, float hi) { f32x2 v = {lo, hi}; bf16x2_t b = __builtin_convertvector(v, bf16x2_t); return *(unsigned*)&b; }
; __device__ __forceinline__ float lo16(unsigned w) { return __uint_as_float(w << 16); }
; __device__ __forceinline__ float hi16(unsigned w) { return __uint_as_float(w & 0xffff0000u); }
; #define SWAIT() asm volatile("s_waitcnt vmcnt(3)" ::: "memory")
; __device__ void phase_attn(const Params& p, char* lds) {
;     ...
;   for (int it = slot; it < nitems / 8; it += per) {
;     const int pair = (it >> 5) * 8 + xcd, qblk = it & 31;
;     const int b = pair >> 4, h = pair & 15;
;     const size_t row0 = (size_t)b * TL;
;     const size_t qrow = row0 + qblk * 256 + wid * 32 + r32;
;     const bf16_t* Kh = KVg + row0 * 2048 + h * 128;
;     const bf16_t* Kp = KPg + row0 * 32;
;     float m_reg = 0.f, l_reg = 0.f;
;     f32x16 o[2];
; #pragma unroll
;     for (int dd = 0; dd < 2; ++dd)
; #pragma unroll
;       for (int r = 0; r < 16; ++r) o[dd][r] = 0.f;
;     bf16x8 qr[6];
;     {
;       const bf16_t* Qw = Qg + qrow * 1536 + h * 96 + hi * 8;
; #pragma unroll
;       for (int d0 = 0; d0 < 6; ++d0) qr[d0] = *(const bf16x8*)(Qw + d0 * 16);
;       const int t = qblk * 256 + wid * 32 + r32;
;       const f32x2* tb = rope + (hi ? (t & 63) : (t >> 6)) * 8;
;       const u32x4 x1 = *(const u32x4*)&qr[4], x2 = *(const u32x4*)&qr[5];
;       u32x4 n1, n2;
; #pragma unroll
;       for (int q = 0; q < 4; ++q) {
;         const f32x2 csA = tb[2 * q], csB = tb[2 * q + 1];
;         const float a0 = lo16(x1[q]), a1 = hi16(x1[q]), b0 = lo16(x2[q]), b1 = hi16(x2[q]);
;         n1[q] = cvtpk(a0 * csA[0] - b0 * csA[1], a1 * csB[0] - b1 * csB[1]);
;         n2[q] = cvtpk(a0 * csA[1] + b0 * csA[0], a1 * csB[1] + b1 * csB[0]);
;       }
;       qr[4] = *(bf16x8*)&n1; qr[5] = *(bf16x8*)&n2;
;     }
;     struct { bf16x8 vs, ks, ps; } sr_[2];
;     ...
;     f32x16 pA0, pA1, pB0, pB1; float alA, alB; bf16x8 pa0, pa1, pa2, pa3;
;     constexpr int NT = TL / 64;
;     SLOAD(0, 0); asm volatile("s_waitcnt vmcnt(0)" ::: "memory"); SWRITE(0, 0); __syncthreads();
;     at_qkt(pA0, pA1, K_lds, qr, r32, hi, 0.f); at_partialSM(pA0, pA1, m_reg, alA, true);
;     SLOAD(1, 64); SLOAD(0, 128);
;     SWAIT(); SWRITE(1, 1); __syncthreads();
.Lat_item:
	s_lshr_b32 s16, s12, 5
	s_lshl_b32 s16, s16, 3
	s_add_i32 s16, s16, s43
	s_and_b32 s20, s12, 31
	s_lshr_b32 s22, s16, 4
	s_and_b32 s21, s16, 15
	s_mul_i32 s17, s22, 0x2100000
	s_lshl_b32 s18, s21, 8
	s_add_i32 s17, s17, s18
	s_add_u32 s17, s17, 0x29400000
	s_mov_b32 s0, s17
	s_add_u32 s4, s86, s17
	s_addc_u32 s5, s87, 0
	s_mul_i32 s17, s22, 0x84000
	s_add_u32 s17, s17, 0x1de80000
	s_mov_b32 s1, s17
	s_add_u32 s6, s86, s17
	s_addc_u32 s7, s87, 0
	s_mul_i32 s17, s22, 0x2100
	s_lshl_b32 s18, s20, 8
	s_add_i32 s17, s17, s18
	s_mul_i32 s18, s17, 0xc00
	s_mul_i32 s19, s21, 0xc0
	s_add_i32 s18, s18, s19
	s_add_u32 s18, s18, 0x8400000
	s_add_u32 s10, s86, s18
	s_addc_u32 s11, s87, 0
	s_lshl_b32 s18, s17, 11
	s_lshl_b32 s19, s21, 7
	s_add_i32 s18, s18, s19
	s_add_u32 s18, s18, 0x21000000
	s_add_u32 s28, s86, s18
	s_addc_u32 s29, s87, 0
	global_load_dwordx4 v[80:83], v234, s[10:11] offset:0
	global_load_dwordx4 v[84:87], v234, s[10:11] offset:32
	global_load_dwordx4 v[88:91], v234, s[10:11] offset:64
	global_load_dwordx4 v[92:95], v234, s[10:11] offset:96
	global_load_dwordx4 v[96:99], v234, s[10:11] offset:128
	global_load_dwordx4 v[100:103], v234, s[10:11] offset:160
	s_and_b32 s16, s14, 1
	s_lshl_b32 s16, s16, 5
	v_and_b32_e32 v183, 31, v178
	v_add_u32_e32 v183, s16, v183
	v_lshlrev_b32_e32 v183, 6, v183
	s_lshl_b32 s16, s20, 2
	s_lshr_b32 s17, s14, 1
	s_add_i32 s16, s16, s17
	s_lshl_b32 s16, s16, 6
	v_mov_b32_e32 v228, s16
	v_and_b32_e32 v229, 32, v178
	v_cmp_ne_u32_e32 vcc, 0, v229
	s_nop 1
	v_cndmask_b32_e32 v183, v228, v183, vcc
	global_load_dwordx4 v[32:35], v183, s[34:35] offset:0
	global_load_dwordx4 v[36:39], v183, s[34:35] offset:16
	global_load_dwordx4 v[40:43], v183, s[34:35] offset:32
	global_load_dwordx4 v[44:47], v183, s[34:35] offset:48
	s_barrier
	s_mov_b64 s[36:37], s[4:5]
	v_mov_b32_e32 v230, s1
	v_mov_b32_e32 v246, s0
	v_cndmask_b32_e64 v246, v246, v230, s[44:45]
	v_add_u32_e32 v246, v249, v246
	v_mov_b32_e32 v250, s0
	v_cndmask_b32_e64 v250, v250, v230, s[46:47]
	v_add_u32_e32 v250, v253, v250
	s_add_i32 m0, s41, 0x10000
	s_cmp_lt_u32 s14, 5
	global_load_lds_dwordx4 v246, s[86:87]
	v_add_u32_e32 v246, v248, v246
	s_cbranch_scc0 .Lat_kd1
	s_add_i32 m0, s30, 0x10000
	s_nop 0
	global_load_lds_dwordx4 v250, s[86:87]
.Lat_kd1:
	v_add_u32_e32 v250, v252, v250
	s_add_i32 m0, s41, 0x13400
	s_cmp_lt_u32 s14, 5
	global_load_lds_dwordx4 v246, s[86:87]
	v_add_u32_e32 v246, v248, v246
	s_cbranch_scc0 .Lat_kd2
	s_add_i32 m0, s30, 0x13400
	s_nop 0
	global_load_lds_dwordx4 v250, s[86:87]
.Lat_kd2:
	v_add_u32_e32 v250, v252, v250
	s_add_i32 m0, s41, 0x16800
	s_cmp_lt_u32 s14, 5
	global_load_lds_dwordx4 v246, s[86:87]
	v_add_u32_e32 v246, v248, v246
	s_cbranch_scc0 .Lat_kd3
	s_add_i32 m0, s30, 0x16800
	s_nop 0
	global_load_lds_dwordx4 v250, s[86:87]
.Lat_kd3:
	v_add_u32_e32 v250, v252, v250
	s_add_i32 m0, s40, 0x0
	s_nop 0
	global_load_lds_dwordx4 v131, s[36:37]
	s_add_u32 s36, s36, 0x40000
	s_addc_u32 s37, s37, 0
	s_add_i32 m0, s40, 0x4000
	s_nop 0
	global_load_lds_dwordx4 v131, s[36:37]
	s_add_u32 s36, s36, 0x40000
	s_addc_u32 s37, s37, 0
	s_waitcnt vmcnt(0)
	v_lshlrev_b32_e32 v175, 16, v96
	v_and_b32_e32 v183, 0xffff0000, v96
	v_lshlrev_b32_e32 v228, 16, v100
	v_and_b32_e32 v229, 0xffff0000, v100
	v_mul_f32_e32 v230, v228, v33
	v_mul_f32_e32 v174, v229, v35
	v_fma_f32 v230, v175, v32, -v230
	v_fma_f32 v174, v183, v34, -v174
	v_mul_f32_e32 v175, v175, v33
	v_mul_f32_e32 v183, v183, v35
	v_fma_f32 v175, v228, v32, v175
	v_fma_f32 v183, v229, v34, v183
	v_cvt_pk_bf16_f32 v96, v230, v174
	v_cvt_pk_bf16_f32 v100, v175, v183
	v_lshlrev_b32_e32 v175, 16, v97
	v_and_b32_e32 v183, 0xffff0000, v97
	v_lshlrev_b32_e32 v228, 16, v101
	v_and_b32_e32 v229, 0xffff0000, v101
	v_mul_f32_e32 v230, v228, v37
	v_mul_f32_e32 v174, v229, v39
	v_fma_f32 v230, v175, v36, -v230
	v_fma_f32 v174, v183, v38, -v174
	v_mul_f32_e32 v175, v175, v37
	v_mul_f32_e32 v183, v183, v39
	v_fma_f32 v175, v228, v36, v175
	v_fma_f32 v183, v229, v38, v183
	v_cvt_pk_bf16_f32 v97, v230, v174
	v_cvt_pk_bf16_f32 v101, v175, v183
	v_lshlrev_b32_e32 v175, 16, v98
	v_and_b32_e32 v183, 0xffff0000, v98
	v_lshlrev_b32_e32 v228, 16, v102
	v_and_b32_e32 v229, 0xffff0000, v102
	v_mul_f32_e32 v230, v228, v41
	v_mul_f32_e32 v174, v229, v43
	v_fma_f32 v230, v175, v40, -v230
	v_fma_f32 v174, v183, v42, -v174
	v_mul_f32_e32 v175, v175, v41
	v_mul_f32_e32 v183, v183, v43
	v_fma_f32 v175, v228, v40, v175
	v_fma_f32 v183, v229, v42, v183
	v_cvt_pk_bf16_f32 v98, v230, v174
	v_cvt_pk_bf16_f32 v102, v175, v183
	v_lshlrev_b32_e32 v175, 16, v99
	v_and_b32_e32 v183, 0xffff0000, v99
	v_lshlrev_b32_e32 v228, 16, v103
	v_and_b32_e32 v229, 0xffff0000, v103
	v_mul_f32_e32 v230, v228, v45
	v_mul_f32_e32 v174, v229, v47
	v_fma_f32 v230, v175, v44, -v230
	v_fma_f32 v174, v183, v46, -v174
	v_mul_f32_e32 v175, v175, v45
	v_mul_f32_e32 v183, v183, v47
	v_fma_f32 v175, v228, v44, v175
	v_fma_f32 v183, v229, v46, v183
	v_cvt_pk_bf16_f32 v99, v230, v174
	v_cvt_pk_bf16_f32 v103, v175, v183
	v_mov_b32_e32 v0, 0
	v_mov_b32_e32 v1, 0
	v_mov_b32_e32 v2, 0
	v_mov_b32_e32 v3, 0
	v_mov_b32_e32 v4, 0
	v_mov_b32_e32 v5, 0
	v_mov_b32_e32 v6, 0
	v_mov_b32_e32 v7, 0
	v_mov_b32_e32 v8, 0
	v_mov_b32_e32 v9, 0
	v_mov_b32_e32 v10, 0
	v_mov_b32_e32 v11, 0
	v_mov_b32_e32 v12, 0
	v_mov_b32_e32 v13, 0
	v_mov_b32_e32 v14, 0
	v_mov_b32_e32 v15, 0
	v_mov_b32_e32 v16, 0
	v_mov_b32_e32 v17, 0
	v_mov_b32_e32 v18, 0
	v_mov_b32_e32 v19, 0
	v_mov_b32_e32 v20, 0
	v_mov_b32_e32 v21, 0
	v_mov_b32_e32 v22, 0
	v_mov_b32_e32 v23, 0
	v_mov_b32_e32 v24, 0
	v_mov_b32_e32 v25, 0
	v_mov_b32_e32 v26, 0
	v_mov_b32_e32 v27, 0
	v_mov_b32_e32 v28, 0
	v_mov_b32_e32 v29, 0
	v_mov_b32_e32 v30, 0
	v_mov_b32_e32 v31, 0
	v_mov_b32_e32 v173, 0
	s_barrier
	ds_read_b128 v[184:187], v170 offset:0
	ds_read_b128 v[188:191], v170 offset:6656
	ds_read_b128 v[192:195], v170 offset:32
	ds_read_b128 v[196:199], v170 offset:6688
	s_cmp_eq_u32 s15, 0
	s_cbranch_scc1 .Lat_nostag
	s_barrier
; #define MFMA(a, b, c) __builtin_amdgcn_mfma_f32_32x32x16_bf16((a), (b), (c), 0, 0, 0)
; __device__ __forceinline__ void at_partialSM(f32x16& p0, f32x16& p1, float& m_reg, float& alpha, bool force) {
;   float pm = p0[0];
; #pragma unroll
;   for (int r = 1; r < 16; ++r) pm = fmaxf(pm, p0[r]);
; #pragma unroll
;   for (int r = 0; r < 16; ++r) pm = fmaxf(pm, p1[r]);
;   { auto rr = __builtin_amdgcn_permlane32_swap(__float_as_uint(pm), __float_as_uint(pm), false, false);
;     pm = fmaxf(__uint_as_float(rr[0]), __uint_as_float(rr[1])); }
;   if (__builtin_expect(!force && __all(pm <= AT_THR * 1.4426950408889634f), 1)) { alpha = 1.f; }
;   else {
;     const float dlt = force ? pm : fmaxf(pm, 0.f);
;     alpha = force ? 1.f : __builtin_amdgcn_exp2f(-dlt); m_reg += dlt;
; #pragma unroll
;     for (int r = 0; r < 16; ++r) { p0[r] -= dlt; p1[r] -= dlt; }
;   }
; #pragma unroll
;   for (int r = 0; r < 16; ++r) p0[r] = __builtin_amdgcn_exp2f(p0[r]);
; }
; __device__ __forceinline__ void at_finishSM(f32x16& p0, f32x16& p1, float alpha, float& l_reg, bf16x8& pa0, bf16x8& pa1, bf16x8& pa2, bf16x8& pa3) {
; #pragma unroll
;   for (int r = 0; r < 16; ++r) p1[r] = __builtin_amdgcn_exp2f(p1[r]);
;   float ps = 0;
; #pragma unroll
;   for (int r = 0; r < 16; ++r) ps += p0[r];
; #pragma unroll
;   for (int r = 0; r < 16; ++r) ps += p1[r];
;   { auto rr = __builtin_amdgcn_permlane32_swap(__float_as_uint(ps), __float_as_uint(ps), false, false);
;     ps = __uint_as_float(rr[0]) + __uint_as_float(rr[1]); }
;   l_reg = l_reg * alpha + ps;
;     ...
;   PK4(p0, 0, pa0); PK4(p0, 8, pa1); PK4(p1, 0, pa2); PK4(p1, 8, pa3);
;     ...
; }
; __device__ __forceinline__ void at_qkt(f32x16& p0, f32x16& p1, const char* Ks, const bf16x8* qr, int r32, int hi, float negm) {
; #pragma unroll
;   for (int r = 0; r < 16; ++r) { p0[r] = negm; p1[r] = negm; }
; #pragma unroll
;   for (int d0 = 0; d0 < 6; ++d0) {
;     const bf16x8 b0 = *(const bf16x8*)(Ks + r32 * AT_KROW + d0 * 32 + hi * 16);
;     const bf16x8 b1 = *(const bf16x8*)(Ks + (32 + r32) * AT_KROW + d0 * 32 + hi * 16);
;     p0 = MFMA(b0, qr[d0], p0);
;     p1 = MFMA(b1, qr[d0], p1);
;   }
; }
.Lat_nostag:
	ds_read_b128 v[200:203], v170 offset:64
	ds_read_b128 v[204:207], v170 offset:6720
	s_waitcnt lgkmcnt(4)
	v_mfma_f32_32x32x16_bf16 v[32:47], v[184:187], v[80:83], 0
	v_mfma_f32_32x32x16_bf16 v[48:63], v[188:191], v[80:83], 0
	ds_read_b128 v[208:211], v170 offset:96
	ds_read_b128 v[212:215], v170 offset:6752
	s_waitcnt lgkmcnt(4)
	v_mfma_f32_32x32x16_bf16 v[32:47], v[192:195], v[84:87], v[32:47]
	v_mfma_f32_32x32x16_bf16 v[48:63], v[196:199], v[84:87], v[48:63]
	ds_read_b128 v[184:187], v170 offset:128
	ds_read_b128 v[188:191], v170 offset:6784
	s_waitcnt lgkmcnt(4)
	v_mfma_f32_32x32x16_bf16 v[32:47], v[200:203], v[88:91], v[32:47]
	v_mfma_f32_32x32x16_bf16 v[48:63], v[204:207], v[88:91], v[48:63]
	ds_read_b128 v[192:195], v170 offset:160
	ds_read_b128 v[196:199], v170 offset:6816
	s_waitcnt lgkmcnt(4)
	v_mfma_f32_32x32x16_bf16 v[32:47], v[208:211], v[92:95], v[32:47]
	v_mfma_f32_32x32x16_bf16 v[48:63], v[212:215], v[92:95], v[48:63]
	s_waitcnt lgkmcnt(2)
	v_mfma_f32_32x32x16_bf16 v[32:47], v[184:187], v[96:99], v[32:47]
	v_mfma_f32_32x32x16_bf16 v[48:63], v[188:191], v[96:99], v[48:63]
	s_waitcnt lgkmcnt(0)
	v_mfma_f32_32x32x16_bf16 v[32:47], v[192:195], v[100:103], v[32:47]
	v_mfma_f32_32x32x16_bf16 v[48:63], v[196:199], v[100:103], v[48:63]
	s_nop 11
	v_max3_f32 v174, v32, v33, v34
	v_max3_f32 v175, v48, v49, v50
	v_max3_f32 v174, v174, v35, v36
	v_max3_f32 v175, v175, v51, v52
	v_max3_f32 v174, v174, v37, v38
	v_max3_f32 v175, v175, v53, v54
	v_max3_f32 v174, v174, v39, v40
	v_max3_f32 v175, v175, v55, v56
	v_max3_f32 v174, v174, v41, v42
	v_max3_f32 v175, v175, v57, v58
	v_max3_f32 v174, v174, v43, v44
	v_max3_f32 v175, v175, v59, v60
	v_max3_f32 v174, v174, v45, v46
	v_max3_f32 v175, v175, v61, v62
	v_max3_f32 v174, v174, v47, v63
	v_max_f32_e32 v174, v174, v175
	v_mov_b32_e32 v175, v174
	s_nop 1
	v_permlane32_swap_b32_e32 v174, v175
	v_max_f32_e32 v174, v174, v175
	s_barrier
	v_mov_b32_e32 v172, v174
	v_sub_f32_e32 v32, v32, v174
	v_sub_f32_e32 v48, v48, v174
	v_sub_f32_e32 v33, v33, v174
	v_sub_f32_e32 v49, v49, v174
	v_sub_f32_e32 v34, v34, v174
	v_sub_f32_e32 v50, v50, v174
	v_sub_f32_e32 v35, v35, v174
	v_sub_f32_e32 v51, v51, v174
	v_sub_f32_e32 v36, v36, v174
	v_sub_f32_e32 v52, v52, v174
	v_sub_f32_e32 v37, v37, v174
	v_sub_f32_e32 v53, v53, v174
	v_sub_f32_e32 v38, v38, v174
	v_sub_f32_e32 v54, v54, v174
	v_sub_f32_e32 v39, v39, v174
	v_sub_f32_e32 v55, v55, v174
	v_sub_f32_e32 v40, v40, v174
	v_sub_f32_e32 v56, v56, v174
	v_sub_f32_e32 v41, v41, v174
	v_sub_f32_e32 v57, v57, v174
	v_sub_f32_e32 v42, v42, v174
	v_sub_f32_e32 v58, v58, v174
	v_sub_f32_e32 v43, v43, v174
	v_sub_f32_e32 v59, v59, v174
	v_sub_f32_e32 v44, v44, v174
	v_sub_f32_e32 v60, v60, v174
	v_sub_f32_e32 v45, v45, v174
	v_sub_f32_e32 v61, v61, v174
	v_sub_f32_e32 v46, v46, v174
	v_sub_f32_e32 v62, v62, v174
	v_sub_f32_e32 v47, v47, v174
	v_sub_f32_e32 v63, v63, v174
	v_sub_f32_e32 v64, 0, v174
	v_sub_f32_e32 v65, 0, v174
	v_sub_f32_e32 v66, 0, v174
	v_sub_f32_e32 v67, 0, v174
	v_sub_f32_e32 v68, 0, v174
	v_sub_f32_e32 v69, 0, v174
	v_sub_f32_e32 v70, 0, v174
	v_sub_f32_e32 v71, 0, v174
	v_sub_f32_e32 v72, 0, v174
	v_sub_f32_e32 v73, 0, v174
	v_sub_f32_e32 v74, 0, v174
	v_sub_f32_e32 v75, 0, v174
	v_sub_f32_e32 v76, 0, v174
	v_sub_f32_e32 v77, 0, v174
	v_sub_f32_e32 v78, 0, v174
	v_sub_f32_e32 v79, 0, v174
	s_add_i32 m0, s41, 0x19c00
	s_cmp_lt_u32 s14, 5
	global_load_lds_dwordx4 v246, s[86:87]
	v_add_u32_e32 v246, v248, v246
	s_cbranch_scc0 .Lat_kd4
	s_add_i32 m0, s30, 0x19c00
	s_nop 0
	global_load_lds_dwordx4 v250, s[86:87]
.Lat_kd4:
	v_add_u32_e32 v250, v252, v250
	s_add_i32 m0, s40, 0x8000
	s_nop 0
	global_load_lds_dwordx4 v131, s[36:37]
	s_add_u32 s36, s36, 0x40000
	s_addc_u32 s37, s37, 0
	v_exp_f32_e32 v32, v32
	v_exp_f32_e32 v48, v48
	v_exp_f32_e32 v33, v33
	v_exp_f32_e32 v49, v49
	v_exp_f32_e32 v34, v34
	v_exp_f32_e32 v50, v50
	v_exp_f32_e32 v35, v35
	v_exp_f32_e32 v51, v51
	v_exp_f32_e32 v36, v36
	v_exp_f32_e32 v52, v52
	v_exp_f32_e32 v37, v37
	v_exp_f32_e32 v53, v53
	v_exp_f32_e32 v38, v38
	v_exp_f32_e32 v54, v54
	v_exp_f32_e32 v39, v39
	v_exp_f32_e32 v55, v55
	v_exp_f32_e32 v40, v40
	v_exp_f32_e32 v56, v56
	v_exp_f32_e32 v41, v41
	v_exp_f32_e32 v57, v57
	v_exp_f32_e32 v42, v42
	v_exp_f32_e32 v58, v58
	v_exp_f32_e32 v43, v43
	v_exp_f32_e32 v59, v59
	v_exp_f32_e32 v44, v44
	v_exp_f32_e32 v60, v60
	v_exp_f32_e32 v45, v45
	v_exp_f32_e32 v61, v61
	v_exp_f32_e32 v46, v46
	v_exp_f32_e32 v62, v62
	v_exp_f32_e32 v47, v47
	v_exp_f32_e32 v63, v63
	v_add_f32_e32 v175, v32, v33
	v_add_f32_e32 v174, v48, v49
	v_add_f32_e32 v175, v175, v34
	v_add_f32_e32 v174, v174, v50
	v_add_f32_e32 v175, v175, v35
	v_add_f32_e32 v174, v174, v51
	v_add_f32_e32 v175, v175, v36
	v_add_f32_e32 v174, v174, v52
	v_add_f32_e32 v175, v175, v37
	v_add_f32_e32 v174, v174, v53
	v_add_f32_e32 v175, v175, v38
	v_add_f32_e32 v174, v174, v54
	v_add_f32_e32 v175, v175, v39
	v_add_f32_e32 v174, v174, v55
	v_add_f32_e32 v175, v175, v40
	v_add_f32_e32 v174, v174, v56
	v_add_f32_e32 v175, v175, v41
	v_add_f32_e32 v174, v174, v57
	v_add_f32_e32 v175, v175, v42
	v_add_f32_e32 v174, v174, v58
	v_add_f32_e32 v175, v175, v43
	v_add_f32_e32 v174, v174, v59
	v_add_f32_e32 v175, v175, v44
	v_add_f32_e32 v174, v174, v60
	v_add_f32_e32 v175, v175, v45
	v_add_f32_e32 v174, v174, v61
	v_add_f32_e32 v175, v175, v46
	v_add_f32_e32 v174, v174, v62
	v_add_f32_e32 v175, v175, v47
	v_add_f32_e32 v174, v174, v63
	v_add_f32_e32 v175, v175, v174
	v_add_f32_e32 v173, v173, v175
	v_cvt_pk_bf16_f32 v104, v32, v33
	v_cvt_pk_bf16_f32 v105, v34, v35
	v_cvt_pk_bf16_f32 v106, v36, v37
	v_cvt_pk_bf16_f32 v107, v38, v39
	v_cvt_pk_bf16_f32 v108, v40, v41
	v_cvt_pk_bf16_f32 v109, v42, v43
	v_cvt_pk_bf16_f32 v110, v44, v45
	v_cvt_pk_bf16_f32 v111, v46, v47
	v_cvt_pk_bf16_f32 v112, v48, v49
	v_cvt_pk_bf16_f32 v113, v50, v51
	v_cvt_pk_bf16_f32 v114, v52, v53
	v_cvt_pk_bf16_f32 v115, v54, v55
	v_cvt_pk_bf16_f32 v116, v56, v57
	v_cvt_pk_bf16_f32 v117, v58, v59
	v_cvt_pk_bf16_f32 v118, v60, v61
	v_cvt_pk_bf16_f32 v119, v62, v63
	ds_read_b128 v[184:187], v170 offset:13312
	ds_read_b128 v[188:191], v170 offset:19968
	ds_read_b128 v[192:195], v170 offset:13344
	ds_read_b128 v[196:199], v170 offset:20000
	s_barrier
	s_mov_b32 s13, 32
; #define MFMA(a, b, c) __builtin_amdgcn_mfma_f32_32x32x16_bf16((a), (b), (c), 0, 0, 0)
; #define SBAR() __builtin_amdgcn_sched_barrier(0)
; #define SWAIT() asm volatile("s_waitcnt vmcnt(3)" ::: "memory")
; __device__ __forceinline__ void at_qkt(f32x16& p0, f32x16& p1, const char* Ks, const bf16x8* qr, int r32, int hi, float negm) {
; #pragma unroll
;   for (int r = 0; r < 16; ++r) { p0[r] = negm; p1[r] = negm; }
; #pragma unroll
;   for (int d0 = 0; d0 < 6; ++d0) {
;     const bf16x8 b0 = *(const bf16x8*)(Ks + r32 * AT_KROW + d0 * 32 + hi * 16);
;     const bf16x8 b1 = *(const bf16x8*)(Ks + (32 + r32) * AT_KROW + d0 * 32 + hi * 16);
;     p0 = MFMA(b0, qr[d0], p0);
;     p1 = MFMA(b1, qr[d0], p1);
;   }
; }
; __device__ __forceinline__ int v_st(int k, int c) { const int kk = (k & ~0xC) | ((k & 4) << 1) | ((k & 8) >> 1); return ((kk >> 3) * 4 + (c >> 5)) * 512 + ((kk & 7) * 32 + (c & 31)) * 2; }
; __device__ __forceinline__ int v_rd_base(int lane) { return ((lane & 3) << 3) | (((lane >> 2) & 3) << 6) | (((lane >> 4) & 1) << 5) | (((lane >> 5) & 1) << 8); }
; template <int OFF> __device__ __forceinline__ s16x4 tr_read(int vb) {
;   s16x4 r; asm volatile("ds_read_b64_tr_b16 %0, %1 offset:%2" : "=&v"(r) : "v"(vb), "i"(OFF) : "memory"); return r;
; }
; template <int D0> __device__ __forceinline__ void pv_one(f32x16& od, int vb, bf16x8 pa0, bf16x8 pa1, bf16x8 pa2, bf16x8 pa3) {
;   const s16x4 l0 = tr_read<v_rd_off(D0, 0, 0)>(vb), h0 = tr_read<v_rd_off(D0, 0, 1)>(vb), l1 = tr_read<v_rd_off(D0, 1, 0)>(vb), h1 = tr_read<v_rd_off(D0, 1, 1)>(vb);
;   const s16x4 l2 = tr_read<v_rd_off(D0, 2, 0)>(vb), h2 = tr_read<v_rd_off(D0, 2, 1)>(vb), l3 = tr_read<v_rd_off(D0, 3, 0)>(vb), h3 = tr_read<v_rd_off(D0, 3, 1)>(vb);
;   asm volatile("s_waitcnt lgkmcnt(0)" ::: "memory"); SBAR();
;     ...
;   od = MFMA(pa0, PK(l0, h0), od);
;   od = MFMA(pa1, PK(l1, h1), od);
;   od = MFMA(pa2, PK(l2, h2), od);
;   od = MFMA(pa3, PK(l3, h3), od);
;     ...
; }
; __device__ void phase_attn(const Params& p, char* lds) {
;     ...
;     for (int j = 1; j + 1 < NT; j += 2) {
;       SBAR(); at_qkt(pB0, pB1, K_lds + AT_SHMK, qr, r32, hi, -m_reg);
;       at_finishSM(pA0, pA1, alA, l_reg, pa0, pa1, pa2, pa3); SBAR();
;       SLOAD(1, (j + 2) * 64); SBAR();
;       pv_d0(o, vb0, pa0, pa1, pa2, pa3); at_partialSM(pB0, pB1, m_reg, alB, false);
;       __syncthreads(); SWAIT(); SWRITE(0, 0);
;       RESC(alB); __syncthreads();
.Lat_loop:
	ds_read_b128 v[200:203], v170 offset:13376
	ds_read_b128 v[204:207], v170 offset:20032
	s_waitcnt lgkmcnt(4)
	v_mfma_f32_32x32x16_bf16 v[32:47], v[184:187], v[80:83], v[64:79]
	v_mfma_f32_32x32x16_bf16 v[48:63], v[188:191], v[80:83], v[64:79]
	ds_read_b128 v[208:211], v170 offset:13408
	ds_read_b128 v[212:215], v170 offset:20064
	s_waitcnt lgkmcnt(4)
	v_mfma_f32_32x32x16_bf16 v[32:47], v[192:195], v[84:87], v[32:47]
	v_mfma_f32_32x32x16_bf16 v[48:63], v[196:199], v[84:87], v[48:63]
	ds_read_b128 v[184:187], v170 offset:13440
	ds_read_b128 v[188:191], v170 offset:20096
	s_waitcnt lgkmcnt(4)
	v_mfma_f32_32x32x16_bf16 v[32:47], v[200:203], v[88:91], v[32:47]
	v_mfma_f32_32x32x16_bf16 v[48:63], v[204:207], v[88:91], v[48:63]
	ds_read_b128 v[192:195], v170 offset:13472
	ds_read_b128 v[196:199], v170 offset:20128
	s_waitcnt lgkmcnt(4)
	v_mfma_f32_32x32x16_bf16 v[32:47], v[208:211], v[92:95], v[32:47]
	v_mfma_f32_32x32x16_bf16 v[48:63], v[212:215], v[92:95], v[48:63]
	ds_read_b64_tr_b16 v[148:149], v171 offset:0
	ds_read_b64_tr_b16 v[150:151], v171 offset:2048
	ds_read_b64_tr_b16 v[152:153], v171 offset:4096
	ds_read_b64_tr_b16 v[154:155], v171 offset:6144
	s_waitcnt lgkmcnt(6)
	v_mfma_f32_32x32x16_bf16 v[32:47], v[184:187], v[96:99], v[32:47]
	v_mfma_f32_32x32x16_bf16 v[48:63], v[188:191], v[96:99], v[48:63]
	ds_read_b64_tr_b16 v[156:157], v171 offset:8192
	ds_read_b64_tr_b16 v[158:159], v171 offset:10240
	ds_read_b64_tr_b16 v[216:217], v171 offset:12288
	ds_read_b64_tr_b16 v[218:219], v171 offset:14336
	s_waitcnt lgkmcnt(8)
	v_mfma_f32_32x32x16_bf16 v[32:47], v[192:195], v[100:103], v[32:47]
	v_mfma_f32_32x32x16_bf16 v[48:63], v[196:199], v[100:103], v[48:63]
	ds_read_b64_tr_b16 v[220:221], v171 offset:512
	ds_read_b64_tr_b16 v[222:223], v171 offset:2560
	ds_read_b64_tr_b16 v[224:225], v171 offset:4608
	ds_read_b64_tr_b16 v[226:227], v171 offset:6656
	s_waitcnt lgkmcnt(10)
	v_mfma_f32_32x32x16_bf16 v[0:15], v[104:107], v[148:151], v[0:15]
	s_waitcnt lgkmcnt(8)
	v_mfma_f32_32x32x16_bf16 v[0:15], v[108:111], v[152:155], v[0:15]
	ds_read_b64_tr_b16 v[236:237], v171 offset:8704
	ds_read_b64_tr_b16 v[238:239], v171 offset:10752
	ds_read_b64_tr_b16 v[240:241], v171 offset:12800
	ds_read_b64_tr_b16 v[242:243], v171 offset:14848
	s_waitcnt lgkmcnt(10)
	v_mfma_f32_32x32x16_bf16 v[0:15], v[112:115], v[156:159], v[0:15]
	s_waitcnt lgkmcnt(8)
	v_mfma_f32_32x32x16_bf16 v[0:15], v[116:119], v[216:219], v[0:15]
	s_waitcnt lgkmcnt(6)
	v_mfma_f32_32x32x16_bf16 v[16:31], v[104:107], v[220:223], v[16:31]
	s_waitcnt lgkmcnt(4)
	v_mfma_f32_32x32x16_bf16 v[16:31], v[108:111], v[224:227], v[16:31]
	s_waitcnt lgkmcnt(2)
	v_mfma_f32_32x32x16_bf16 v[16:31], v[112:115], v[236:239], v[16:31]
	s_waitcnt lgkmcnt(0)
	v_mfma_f32_32x32x16_bf16 v[16:31], v[116:119], v[240:243], v[16:31]
	s_barrier
	s_waitcnt vmcnt(0)
	s_add_i32 m0, s41, 0x10000
	s_cmp_lt_u32 s14, 5
	global_load_lds_dwordx4 v246, s[86:87]
	v_add_u32_e32 v246, v248, v246
	s_cbranch_scc0 .Lat_kd5
	s_add_i32 m0, s30, 0x10000
	s_nop 0
	global_load_lds_dwordx4 v250, s[86:87]
.Lat_kd5:
	v_add_u32_e32 v250, v252, v250
	s_add_i32 m0, s40, 0xc000
	s_nop 0
	global_load_lds_dwordx4 v131, s[36:37]
	s_add_u32 s36, s36, 0x40000
	s_addc_u32 s37, s37, 0
	v_exp_f32_e32 v32, v32
	v_exp_f32_e32 v48, v48
	v_exp_f32_e32 v33, v33
	v_exp_f32_e32 v49, v49
	v_exp_f32_e32 v34, v34
	v_exp_f32_e32 v50, v50
	v_exp_f32_e32 v35, v35
	v_exp_f32_e32 v51, v51
	v_exp_f32_e32 v36, v36
	v_exp_f32_e32 v52, v52
	v_exp_f32_e32 v37, v37
	v_exp_f32_e32 v53, v53
	v_exp_f32_e32 v38, v38
	v_exp_f32_e32 v54, v54
	v_exp_f32_e32 v39, v39
	v_exp_f32_e32 v55, v55
	v_exp_f32_e32 v40, v40
	v_exp_f32_e32 v56, v56
	v_exp_f32_e32 v41, v41
	v_exp_f32_e32 v57, v57
	v_exp_f32_e32 v42, v42
	v_exp_f32_e32 v58, v58
	v_exp_f32_e32 v43, v43
	v_exp_f32_e32 v59, v59
	v_exp_f32_e32 v44, v44
	v_exp_f32_e32 v60, v60
	v_exp_f32_e32 v45, v45
	v_exp_f32_e32 v61, v61
	v_exp_f32_e32 v46, v46
	v_exp_f32_e32 v62, v62
	v_exp_f32_e32 v47, v47
	v_exp_f32_e32 v63, v63
	v_add_f32_e32 v175, v32, v33
	v_add_f32_e32 v174, v48, v49
	v_add_f32_e32 v175, v175, v34
	v_add_f32_e32 v174, v174, v50
	v_add_f32_e32 v175, v175, v35
	v_add_f32_e32 v174, v174, v51
	v_add_f32_e32 v175, v175, v36
	v_add_f32_e32 v174, v174, v52
	v_add_f32_e32 v175, v175, v37
	v_add_f32_e32 v174, v174, v53
	v_add_f32_e32 v175, v175, v38
	v_add_f32_e32 v174, v174, v54
	v_add_f32_e32 v175, v175, v39
	v_add_f32_e32 v174, v174, v55
	v_add_f32_e32 v175, v175, v40
	v_add_f32_e32 v174, v174, v56
	v_add_f32_e32 v175, v175, v41
	v_add_f32_e32 v174, v174, v57
	v_add_f32_e32 v175, v175, v42
	v_add_f32_e32 v174, v174, v58
	v_add_f32_e32 v175, v175, v43
	v_add_f32_e32 v174, v174, v59
	v_add_f32_e32 v175, v175, v44
	v_add_f32_e32 v174, v174, v60
	v_add_f32_e32 v175, v175, v45
	v_add_f32_e32 v174, v174, v61
	v_add_f32_e32 v175, v175, v46
	v_add_f32_e32 v174, v174, v62
	v_add_f32_e32 v175, v175, v47
	v_add_f32_e32 v174, v174, v63
	v_add_f32_e32 v175, v175, v174
	v_cmp_ge_f32_e32 vcc, s23, v175
	s_cmp_eq_u64 vcc, exec
	s_cbranch_scc0 .Lat_rare0
; #define MFMA(a, b, c) __builtin_amdgcn_mfma_f32_32x32x16_bf16((a), (b), (c), 0, 0, 0)
; #define SBAR() __builtin_amdgcn_sched_barrier(0)
; #define SWAIT() asm volatile("s_waitcnt vmcnt(3)" ::: "memory")
; __device__ __forceinline__ void at_qkt(f32x16& p0, f32x16& p1, const char* Ks, const bf16x8* qr, int r32, int hi, float negm) {
; #pragma unroll
;   for (int r = 0; r < 16; ++r) { p0[r] = negm; p1[r] = negm; }
; #pragma unroll
;   for (int d0 = 0; d0 < 6; ++d0) {
;     const bf16x8 b0 = *(const bf16x8*)(Ks + r32 * AT_KROW + d0 * 32 + hi * 16);
;     const bf16x8 b1 = *(const bf16x8*)(Ks + (32 + r32) * AT_KROW + d0 * 32 + hi * 16);
;     p0 = MFMA(b0, qr[d0], p0);
;     p1 = MFMA(b1, qr[d0], p1);
;   }
; }
; __device__ __forceinline__ int v_st(int k, int c) { const int kk = (k & ~0xC) | ((k & 4) << 1) | ((k & 8) >> 1); return ((kk >> 3) * 4 + (c >> 5)) * 512 + ((kk & 7) * 32 + (c & 31)) * 2; }
; __device__ __forceinline__ int v_rd_base(int lane) { return ((lane & 3) << 3) | (((lane >> 2) & 3) << 6) | (((lane >> 4) & 1) << 5) | (((lane >> 5) & 1) << 8); }
; template <int OFF> __device__ __forceinline__ s16x4 tr_read(int vb) {
;   s16x4 r; asm volatile("ds_read_b64_tr_b16 %0, %1 offset:%2" : "=&v"(r) : "v"(vb), "i"(OFF) : "memory"); return r;
; }
; template <int D0> __device__ __forceinline__ void pv_one(f32x16& od, int vb, bf16x8 pa0, bf16x8 pa1, bf16x8 pa2, bf16x8 pa3) {
;   const s16x4 l0 = tr_read<v_rd_off(D0, 0, 0)>(vb), h0 = tr_read<v_rd_off(D0, 0, 1)>(vb), l1 = tr_read<v_rd_off(D0, 1, 0)>(vb), h1 = tr_read<v_rd_off(D0, 1, 1)>(vb);
;   const s16x4 l2 = tr_read<v_rd_off(D0, 2, 0)>(vb), h2 = tr_read<v_rd_off(D0, 2, 1)>(vb), l3 = tr_read<v_rd_off(D0, 3, 0)>(vb), h3 = tr_read<v_rd_off(D0, 3, 1)>(vb);
;   asm volatile("s_waitcnt lgkmcnt(0)" ::: "memory"); SBAR();
;     ...
;   od = MFMA(pa0, PK(l0, h0), od);
;   od = MFMA(pa1, PK(l1, h1), od);
;   od = MFMA(pa2, PK(l2, h2), od);
;   od = MFMA(pa3, PK(l3, h3), od);
;     ...
; }
; __device__ void phase_attn(const Params& p, char* lds) {
;     ...
;       SBAR(); at_qkt(pA0, pA1, K_lds, qr, r32, hi, -m_reg);
;       at_finishSM(pB0, pB1, alB, l_reg, pa0, pa1, pa2, pa3); SBAR();
;       if (j + 3 < NT) SLOAD(0, (j + 3) * 64); SBAR();
;       pv_d0(o, vb0 + AT_SHMV, pa0, pa1, pa2, pa3); at_partialSM(pA0, pA1, m_reg, alA, false);
;       __syncthreads(); SWAIT(); SWRITE(1, 1);
;       RESC(alA); __syncthreads();
.Lat_rare0_back:
	v_add_f32_e32 v173, v173, v175
	v_cvt_pk_bf16_f32 v104, v32, v33
	v_cvt_pk_bf16_f32 v105, v34, v35
	v_cvt_pk_bf16_f32 v106, v36, v37
	v_cvt_pk_bf16_f32 v107, v38, v39
	v_cvt_pk_bf16_f32 v108, v40, v41
	v_cvt_pk_bf16_f32 v109, v42, v43
	v_cvt_pk_bf16_f32 v110, v44, v45
	v_cvt_pk_bf16_f32 v111, v46, v47
	v_cvt_pk_bf16_f32 v112, v48, v49
	v_cvt_pk_bf16_f32 v113, v50, v51
	v_cvt_pk_bf16_f32 v114, v52, v53
	v_cvt_pk_bf16_f32 v115, v54, v55
	v_cvt_pk_bf16_f32 v116, v56, v57
	v_cvt_pk_bf16_f32 v117, v58, v59
	v_cvt_pk_bf16_f32 v118, v60, v61
	v_cvt_pk_bf16_f32 v119, v62, v63
	ds_read_b128 v[184:187], v170 offset:26624
	ds_read_b128 v[188:191], v170 offset:33280
	ds_read_b128 v[192:195], v170 offset:26656
	ds_read_b128 v[196:199], v170 offset:33312
	s_barrier
	ds_read_b128 v[200:203], v170 offset:26688
	ds_read_b128 v[204:207], v170 offset:33344
	s_waitcnt lgkmcnt(4)
	v_mfma_f32_32x32x16_bf16 v[32:47], v[184:187], v[80:83], v[64:79]
	v_mfma_f32_32x32x16_bf16 v[48:63], v[188:191], v[80:83], v[64:79]
	ds_read_b128 v[208:211], v170 offset:26720
	ds_read_b128 v[212:215], v170 offset:33376
	s_waitcnt lgkmcnt(4)
	v_mfma_f32_32x32x16_bf16 v[32:47], v[192:195], v[84:87], v[32:47]
	v_mfma_f32_32x32x16_bf16 v[48:63], v[196:199], v[84:87], v[48:63]
	ds_read_b128 v[184:187], v170 offset:26752
	ds_read_b128 v[188:191], v170 offset:33408
	s_waitcnt lgkmcnt(4)
	v_mfma_f32_32x32x16_bf16 v[32:47], v[200:203], v[88:91], v[32:47]
	v_mfma_f32_32x32x16_bf16 v[48:63], v[204:207], v[88:91], v[48:63]
	ds_read_b128 v[192:195], v170 offset:26784
	ds_read_b128 v[196:199], v170 offset:33440
	s_waitcnt lgkmcnt(4)
	v_mfma_f32_32x32x16_bf16 v[32:47], v[208:211], v[92:95], v[32:47]
	v_mfma_f32_32x32x16_bf16 v[48:63], v[212:215], v[92:95], v[48:63]
	ds_read_b64_tr_b16 v[148:149], v171 offset:16384
	ds_read_b64_tr_b16 v[150:151], v171 offset:18432
	ds_read_b64_tr_b16 v[152:153], v171 offset:20480
	ds_read_b64_tr_b16 v[154:155], v171 offset:22528
	s_waitcnt lgkmcnt(6)
	v_mfma_f32_32x32x16_bf16 v[32:47], v[184:187], v[96:99], v[32:47]
	v_mfma_f32_32x32x16_bf16 v[48:63], v[188:191], v[96:99], v[48:63]
	ds_read_b64_tr_b16 v[156:157], v171 offset:24576
	ds_read_b64_tr_b16 v[158:159], v171 offset:26624
	ds_read_b64_tr_b16 v[216:217], v171 offset:28672
	ds_read_b64_tr_b16 v[218:219], v171 offset:30720
	s_waitcnt lgkmcnt(8)
	v_mfma_f32_32x32x16_bf16 v[32:47], v[192:195], v[100:103], v[32:47]
	v_mfma_f32_32x32x16_bf16 v[48:63], v[196:199], v[100:103], v[48:63]
	ds_read_b64_tr_b16 v[220:221], v171 offset:16896
	ds_read_b64_tr_b16 v[222:223], v171 offset:18944
	ds_read_b64_tr_b16 v[224:225], v171 offset:20992
	ds_read_b64_tr_b16 v[226:227], v171 offset:23040
	s_waitcnt lgkmcnt(10)
	v_mfma_f32_32x32x16_bf16 v[0:15], v[104:107], v[148:151], v[0:15]
	s_waitcnt lgkmcnt(8)
	v_mfma_f32_32x32x16_bf16 v[0:15], v[108:111], v[152:155], v[0:15]
	ds_read_b64_tr_b16 v[236:237], v171 offset:25088
	ds_read_b64_tr_b16 v[238:239], v171 offset:27136
	ds_read_b64_tr_b16 v[240:241], v171 offset:29184
	ds_read_b64_tr_b16 v[242:243], v171 offset:31232
	s_waitcnt lgkmcnt(10)
	v_mfma_f32_32x32x16_bf16 v[0:15], v[112:115], v[156:159], v[0:15]
	s_waitcnt lgkmcnt(8)
	v_mfma_f32_32x32x16_bf16 v[0:15], v[116:119], v[216:219], v[0:15]
	s_waitcnt lgkmcnt(6)
	v_mfma_f32_32x32x16_bf16 v[16:31], v[104:107], v[220:223], v[16:31]
	s_waitcnt lgkmcnt(4)
	v_mfma_f32_32x32x16_bf16 v[16:31], v[108:111], v[224:227], v[16:31]
	s_waitcnt lgkmcnt(2)
	v_mfma_f32_32x32x16_bf16 v[16:31], v[112:115], v[236:239], v[16:31]
	s_waitcnt lgkmcnt(0)
	v_mfma_f32_32x32x16_bf16 v[16:31], v[116:119], v[240:243], v[16:31]
	s_barrier
	s_waitcnt vmcnt(0)
	s_add_i32 m0, s41, 0x13400
	s_cmp_lt_u32 s14, 5
	global_load_lds_dwordx4 v246, s[86:87]
	v_add_u32_e32 v246, v248, v246
	s_cbranch_scc0 .Lat_kd6
	s_add_i32 m0, s30, 0x13400
	s_nop 0
	global_load_lds_dwordx4 v250, s[86:87]
.Lat_kd6:
	v_add_u32_e32 v250, v252, v250
	s_add_i32 m0, s40, 0x0
	s_nop 0
	global_load_lds_dwordx4 v131, s[36:37]
	s_add_u32 s36, s36, 0x40000
	s_addc_u32 s37, s37, 0
	v_exp_f32_e32 v32, v32
	v_exp_f32_e32 v48, v48
	v_exp_f32_e32 v33, v33
	v_exp_f32_e32 v49, v49
	v_exp_f32_e32 v34, v34
	v_exp_f32_e32 v50, v50
	v_exp_f32_e32 v35, v35
	v_exp_f32_e32 v51, v51
	v_exp_f32_e32 v36, v36
	v_exp_f32_e32 v52, v52
	v_exp_f32_e32 v37, v37
	v_exp_f32_e32 v53, v53
	v_exp_f32_e32 v38, v38
	v_exp_f32_e32 v54, v54
	v_exp_f32_e32 v39, v39
	v_exp_f32_e32 v55, v55
	v_exp_f32_e32 v40, v40
	v_exp_f32_e32 v56, v56
	v_exp_f32_e32 v41, v41
	v_exp_f32_e32 v57, v57
	v_exp_f32_e32 v42, v42
	v_exp_f32_e32 v58, v58
	v_exp_f32_e32 v43, v43
	v_exp_f32_e32 v59, v59
	v_exp_f32_e32 v44, v44
	v_exp_f32_e32 v60, v60
	v_exp_f32_e32 v45, v45
	v_exp_f32_e32 v61, v61
	v_exp_f32_e32 v46, v46
	v_exp_f32_e32 v62, v62
	v_exp_f32_e32 v47, v47
	v_exp_f32_e32 v63, v63
	v_add_f32_e32 v175, v32, v33
	v_add_f32_e32 v174, v48, v49
	v_add_f32_e32 v175, v175, v34
	v_add_f32_e32 v174, v174, v50
	v_add_f32_e32 v175, v175, v35
	v_add_f32_e32 v174, v174, v51
	v_add_f32_e32 v175, v175, v36
	v_add_f32_e32 v174, v174, v52
	v_add_f32_e32 v175, v175, v37
	v_add_f32_e32 v174, v174, v53
	v_add_f32_e32 v175, v175, v38
	v_add_f32_e32 v174, v174, v54
	v_add_f32_e32 v175, v175, v39
	v_add_f32_e32 v174, v174, v55
	v_add_f32_e32 v175, v175, v40
	v_add_f32_e32 v174, v174, v56
	v_add_f32_e32 v175, v175, v41
	v_add_f32_e32 v174, v174, v57
	v_add_f32_e32 v175, v175, v42
	v_add_f32_e32 v174, v174, v58
	v_add_f32_e32 v175, v175, v43
	v_add_f32_e32 v174, v174, v59
	v_add_f32_e32 v175, v175, v44
	v_add_f32_e32 v174, v174, v60
	v_add_f32_e32 v175, v175, v45
	v_add_f32_e32 v174, v174, v61
	v_add_f32_e32 v175, v175, v46
	v_add_f32_e32 v174, v174, v62
	v_add_f32_e32 v175, v175, v47
	v_add_f32_e32 v174, v174, v63
	v_add_f32_e32 v175, v175, v174
	v_cmp_ge_f32_e32 vcc, s23, v175
	s_cmp_eq_u64 vcc, exec
	s_cbranch_scc0 .Lat_rare1
; #define MFMA(a, b, c) __builtin_amdgcn_mfma_f32_32x32x16_bf16((a), (b), (c), 0, 0, 0)
; #define SBAR() __builtin_amdgcn_sched_barrier(0)
; #define SWAIT() asm volatile("s_waitcnt vmcnt(3)" ::: "memory")
; __device__ __forceinline__ void at_qkt(f32x16& p0, f32x16& p1, const char* Ks, const bf16x8* qr, int r32, int hi, float negm) {
; #pragma unroll
;   for (int r = 0; r < 16; ++r) { p0[r] = negm; p1[r] = negm; }
; #pragma unroll
;   for (int d0 = 0; d0 < 6; ++d0) {
;     const bf16x8 b0 = *(const bf16x8*)(Ks + r32 * AT_KROW + d0 * 32 + hi * 16);
;     const bf16x8 b1 = *(const bf16x8*)(Ks + (32 + r32) * AT_KROW + d0 * 32 + hi * 16);
;     p0 = MFMA(b0, qr[d0], p0);
;     p1 = MFMA(b1, qr[d0], p1);
;   }
; }
; __device__ __forceinline__ int v_st(int k, int c) { const int kk = (k & ~0xC) | ((k & 4) << 1) | ((k & 8) >> 1); return ((kk >> 3) * 4 + (c >> 5)) * 512 + ((kk & 7) * 32 + (c & 31)) * 2; }
; __device__ __forceinline__ int v_rd_base(int lane) { return ((lane & 3) << 3) | (((lane >> 2) & 3) << 6) | (((lane >> 4) & 1) << 5) | (((lane >> 5) & 1) << 8); }
; template <int OFF> __device__ __forceinline__ s16x4 tr_read(int vb) {
;   s16x4 r; asm volatile("ds_read_b64_tr_b16 %0, %1 offset:%2" : "=&v"(r) : "v"(vb), "i"(OFF) : "memory"); return r;
; }
; template <int D0> __device__ __forceinline__ void pv_one(f32x16& od, int vb, bf16x8 pa0, bf16x8 pa1, bf16x8 pa2, bf16x8 pa3) {
;   const s16x4 l0 = tr_read<v_rd_off(D0, 0, 0)>(vb), h0 = tr_read<v_rd_off(D0, 0, 1)>(vb), l1 = tr_read<v_rd_off(D0, 1, 0)>(vb), h1 = tr_read<v_rd_off(D0, 1, 1)>(vb);
;   const s16x4 l2 = tr_read<v_rd_off(D0, 2, 0)>(vb), h2 = tr_read<v_rd_off(D0, 2, 1)>(vb), l3 = tr_read<v_rd_off(D0, 3, 0)>(vb), h3 = tr_read<v_rd_off(D0, 3, 1)>(vb);
;   asm volatile("s_waitcnt lgkmcnt(0)" ::: "memory"); SBAR();
;     ...
;   od = MFMA(pa0, PK(l0, h0), od);
;   od = MFMA(pa1, PK(l1, h1), od);
;   od = MFMA(pa2, PK(l2, h2), od);
;   od = MFMA(pa3, PK(l3, h3), od);
;     ...
; }
; __device__ void phase_attn(const Params& p, char* lds) {
;     ...
;     for (int j = 1; j + 1 < NT; j += 2) {
;       SBAR(); at_qkt(pB0, pB1, K_lds + AT_SHMK, qr, r32, hi, -m_reg);
;       at_finishSM(pA0, pA1, alA, l_reg, pa0, pa1, pa2, pa3); SBAR();
;       SLOAD(1, (j + 2) * 64); SBAR();
;       pv_d0(o, vb0, pa0, pa1, pa2, pa3); at_partialSM(pB0, pB1, m_reg, alB, false);
;       __syncthreads(); SWAIT(); SWRITE(0, 0);
;       RESC(alB); __syncthreads();
.Lat_rare1_back:
	v_add_f32_e32 v173, v173, v175
	v_cvt_pk_bf16_f32 v104, v32, v33
	v_cvt_pk_bf16_f32 v105, v34, v35
	v_cvt_pk_bf16_f32 v106, v36, v37
	v_cvt_pk_bf16_f32 v107, v38, v39
	v_cvt_pk_bf16_f32 v108, v40, v41
	v_cvt_pk_bf16_f32 v109, v42, v43
	v_cvt_pk_bf16_f32 v110, v44, v45
	v_cvt_pk_bf16_f32 v111, v46, v47
	v_cvt_pk_bf16_f32 v112, v48, v49
	v_cvt_pk_bf16_f32 v113, v50, v51
	v_cvt_pk_bf16_f32 v114, v52, v53
	v_cvt_pk_bf16_f32 v115, v54, v55
	v_cvt_pk_bf16_f32 v116, v56, v57
	v_cvt_pk_bf16_f32 v117, v58, v59
	v_cvt_pk_bf16_f32 v118, v60, v61
	v_cvt_pk_bf16_f32 v119, v62, v63
	ds_read_b128 v[184:187], v170 offset:39936
	ds_read_b128 v[188:191], v170 offset:46592
	ds_read_b128 v[192:195], v170 offset:39968
	ds_read_b128 v[196:199], v170 offset:46624
	s_barrier
	ds_read_b128 v[200:203], v170 offset:40000
	ds_read_b128 v[204:207], v170 offset:46656
	s_waitcnt lgkmcnt(4)
	v_mfma_f32_32x32x16_bf16 v[32:47], v[184:187], v[80:83], v[64:79]
	v_mfma_f32_32x32x16_bf16 v[48:63], v[188:191], v[80:83], v[64:79]
	ds_read_b128 v[208:211], v170 offset:40032
	ds_read_b128 v[212:215], v170 offset:46688
	s_waitcnt lgkmcnt(4)
	v_mfma_f32_32x32x16_bf16 v[32:47], v[192:195], v[84:87], v[32:47]
	v_mfma_f32_32x32x16_bf16 v[48:63], v[196:199], v[84:87], v[48:63]
	ds_read_b128 v[184:187], v170 offset:40064
	ds_read_b128 v[188:191], v170 offset:46720
	s_waitcnt lgkmcnt(4)
	v_mfma_f32_32x32x16_bf16 v[32:47], v[200:203], v[88:91], v[32:47]
	v_mfma_f32_32x32x16_bf16 v[48:63], v[204:207], v[88:91], v[48:63]
	ds_read_b128 v[192:195], v170 offset:40096
	ds_read_b128 v[196:199], v170 offset:46752
	s_waitcnt lgkmcnt(4)
	v_mfma_f32_32x32x16_bf16 v[32:47], v[208:211], v[92:95], v[32:47]
	v_mfma_f32_32x32x16_bf16 v[48:63], v[212:215], v[92:95], v[48:63]
	ds_read_b64_tr_b16 v[148:149], v171 offset:32768
	ds_read_b64_tr_b16 v[150:151], v171 offset:34816
	ds_read_b64_tr_b16 v[152:153], v171 offset:36864
	ds_read_b64_tr_b16 v[154:155], v171 offset:38912
	s_waitcnt lgkmcnt(6)
	v_mfma_f32_32x32x16_bf16 v[32:47], v[184:187], v[96:99], v[32:47]
	v_mfma_f32_32x32x16_bf16 v[48:63], v[188:191], v[96:99], v[48:63]
	ds_read_b64_tr_b16 v[156:157], v171 offset:40960
	ds_read_b64_tr_b16 v[158:159], v171 offset:43008
	ds_read_b64_tr_b16 v[216:217], v171 offset:45056
	ds_read_b64_tr_b16 v[218:219], v171 offset:47104
	s_waitcnt lgkmcnt(8)
	v_mfma_f32_32x32x16_bf16 v[32:47], v[192:195], v[100:103], v[32:47]
	v_mfma_f32_32x32x16_bf16 v[48:63], v[196:199], v[100:103], v[48:63]
	ds_read_b64_tr_b16 v[220:221], v171 offset:33280
	ds_read_b64_tr_b16 v[222:223], v171 offset:35328
	ds_read_b64_tr_b16 v[224:225], v171 offset:37376
	ds_read_b64_tr_b16 v[226:227], v171 offset:39424
	s_waitcnt lgkmcnt(10)
	v_mfma_f32_32x32x16_bf16 v[0:15], v[104:107], v[148:151], v[0:15]
	s_waitcnt lgkmcnt(8)
	v_mfma_f32_32x32x16_bf16 v[0:15], v[108:111], v[152:155], v[0:15]
	ds_read_b64_tr_b16 v[236:237], v171 offset:41472
	ds_read_b64_tr_b16 v[238:239], v171 offset:43520
	ds_read_b64_tr_b16 v[240:241], v171 offset:45568
	ds_read_b64_tr_b16 v[242:243], v171 offset:47616
	s_waitcnt lgkmcnt(10)
	v_mfma_f32_32x32x16_bf16 v[0:15], v[112:115], v[156:159], v[0:15]
	s_waitcnt lgkmcnt(8)
	v_mfma_f32_32x32x16_bf16 v[0:15], v[116:119], v[216:219], v[0:15]
	s_waitcnt lgkmcnt(6)
	v_mfma_f32_32x32x16_bf16 v[16:31], v[104:107], v[220:223], v[16:31]
	s_waitcnt lgkmcnt(4)
	v_mfma_f32_32x32x16_bf16 v[16:31], v[108:111], v[224:227], v[16:31]
	s_waitcnt lgkmcnt(2)
	v_mfma_f32_32x32x16_bf16 v[16:31], v[112:115], v[236:239], v[16:31]
	s_waitcnt lgkmcnt(0)
	v_mfma_f32_32x32x16_bf16 v[16:31], v[116:119], v[240:243], v[16:31]
	s_barrier
	s_waitcnt vmcnt(0)
	s_add_i32 m0, s41, 0x16800
	s_cmp_lt_u32 s14, 5
	global_load_lds_dwordx4 v246, s[86:87]
	v_add_u32_e32 v246, v248, v246
	s_cbranch_scc0 .Lat_kd7
	s_add_i32 m0, s30, 0x16800
	s_nop 0
	global_load_lds_dwordx4 v250, s[86:87]
.Lat_kd7:
	v_add_u32_e32 v250, v252, v250
	s_add_i32 m0, s40, 0x4000
	s_nop 0
	global_load_lds_dwordx4 v131, s[36:37]
	s_add_u32 s36, s36, 0x40000
	s_addc_u32 s37, s37, 0
	v_exp_f32_e32 v32, v32
	v_exp_f32_e32 v48, v48
	v_exp_f32_e32 v33, v33
	v_exp_f32_e32 v49, v49
	v_exp_f32_e32 v34, v34
	v_exp_f32_e32 v50, v50
	v_exp_f32_e32 v35, v35
	v_exp_f32_e32 v51, v51
	v_exp_f32_e32 v36, v36
	v_exp_f32_e32 v52, v52
	v_exp_f32_e32 v37, v37
	v_exp_f32_e32 v53, v53
	v_exp_f32_e32 v38, v38
	v_exp_f32_e32 v54, v54
	v_exp_f32_e32 v39, v39
	v_exp_f32_e32 v55, v55
	v_exp_f32_e32 v40, v40
	v_exp_f32_e32 v56, v56
	v_exp_f32_e32 v41, v41
	v_exp_f32_e32 v57, v57
	v_exp_f32_e32 v42, v42
	v_exp_f32_e32 v58, v58
	v_exp_f32_e32 v43, v43
	v_exp_f32_e32 v59, v59
	v_exp_f32_e32 v44, v44
	v_exp_f32_e32 v60, v60
	v_exp_f32_e32 v45, v45
	v_exp_f32_e32 v61, v61
	v_exp_f32_e32 v46, v46
	v_exp_f32_e32 v62, v62
	v_exp_f32_e32 v47, v47
	v_exp_f32_e32 v63, v63
	v_add_f32_e32 v175, v32, v33
	v_add_f32_e32 v174, v48, v49
	v_add_f32_e32 v175, v175, v34
	v_add_f32_e32 v174, v174, v50
	v_add_f32_e32 v175, v175, v35
	v_add_f32_e32 v174, v174, v51
	v_add_f32_e32 v175, v175, v36
	v_add_f32_e32 v174, v174, v52
	v_add_f32_e32 v175, v175, v37
	v_add_f32_e32 v174, v174, v53
	v_add_f32_e32 v175, v175, v38
	v_add_f32_e32 v174, v174, v54
	v_add_f32_e32 v175, v175, v39
	v_add_f32_e32 v174, v174, v55
	v_add_f32_e32 v175, v175, v40
	v_add_f32_e32 v174, v174, v56
	v_add_f32_e32 v175, v175, v41
	v_add_f32_e32 v174, v174, v57
	v_add_f32_e32 v175, v175, v42
	v_add_f32_e32 v174, v174, v58
	v_add_f32_e32 v175, v175, v43
	v_add_f32_e32 v174, v174, v59
	v_add_f32_e32 v175, v175, v44
	v_add_f32_e32 v174, v174, v60
	v_add_f32_e32 v175, v175, v45
	v_add_f32_e32 v174, v174, v61
	v_add_f32_e32 v175, v175, v46
	v_add_f32_e32 v174, v174, v62
	v_add_f32_e32 v175, v175, v47
	v_add_f32_e32 v174, v174, v63
	v_add_f32_e32 v175, v175, v174
	v_cmp_ge_f32_e32 vcc, s23, v175
	s_cmp_eq_u64 vcc, exec
	s_cbranch_scc0 .Lat_rare2
; __device__ __forceinline__ void at_finishSM(f32x16& p0, f32x16& p1, float alpha, float& l_reg, bf16x8& pa0, bf16x8& pa1, bf16x8& pa2, bf16x8& pa3) {
; #pragma unroll
;   for (int r = 0; r < 16; ++r) p1[r] = __builtin_amdgcn_exp2f(p1[r]);
;   float ps = 0;
; #pragma unroll
;   for (int r = 0; r < 16; ++r) ps += p0[r];
; #pragma unroll
;   for (int r = 0; r < 16; ++r) ps += p1[r];
;   { auto rr = __builtin_amdgcn_permlane32_swap(__float_as_uint(ps), __float_as_uint(ps), false, false);
;     ps = __uint_as_float(rr[0]) + __uint_as_float(rr[1]); }
;   l_reg = l_reg * alpha + ps;
;     ...
;   PK4(p0, 0, pa0); PK4(p0, 8, pa1); PK4(p1, 0, pa2); PK4(p1, 8, pa3);
;     ...
; }
; __device__ __forceinline__ void at_qkt(f32x16& p0, f32x16& p1, const char* Ks, const bf16x8* qr, int r32, int hi, float negm) {
; #pragma unroll
;   for (int r = 0; r < 16; ++r) { p0[r] = negm; p1[r] = negm; }
; #pragma unroll
;   for (int d0 = 0; d0 < 6; ++d0) {
;     const bf16x8 b0 = *(const bf16x8*)(Ks + r32 * AT_KROW + d0 * 32 + hi * 16);
;     const bf16x8 b1 = *(const bf16x8*)(Ks + (32 + r32) * AT_KROW + d0 * 32 + hi * 16);
;     p0 = MFMA(b0, qr[d0], p0);
;     p1 = MFMA(b1, qr[d0], p1);
;   }
; }
; __device__ __forceinline__ int v_st(int k, int c) { const int kk = (k & ~0xC) | ((k & 4) << 1) | ((k & 8) >> 1); return ((kk >> 3) * 4 + (c >> 5)) * 512 + ((kk & 7) * 32 + (c & 31)) * 2; }
; __device__ __forceinline__ int v_rd_base(int lane) { return ((lane & 3) << 3) | (((lane >> 2) & 3) << 6) | (((lane >> 4) & 1) << 5) | (((lane >> 5) & 1) << 8); }
; __device__ void phase_attn(const Params& p, char* lds) {
;     ...
;     for (int j = 1; j + 1 < NT; j += 2) {
;       SBAR(); at_qkt(pB0, pB1, K_lds + AT_SHMK, qr, r32, hi, -m_reg);
;       at_finishSM(pA0, pA1, alA, l_reg, pa0, pa1, pa2, pa3); SBAR();
;       SLOAD(1, (j + 2) * 64); SBAR();
;       pv_d0(o, vb0, pa0, pa1, pa2, pa3); at_partialSM(pB0, pB1, m_reg, alB, false);
;       __syncthreads(); SWAIT(); SWRITE(0, 0);
;       RESC(alB); __syncthreads();
;       SBAR(); at_qkt(pA0, pA1, K_lds, qr, r32, hi, -m_reg);
;       at_finishSM(pB0, pB1, alB, l_reg, pa0, pa1, pa2, pa3); SBAR();
;       if (j + 3 < NT) SLOAD(0, (j + 3) * 64); SBAR();
;       pv_d0(o, vb0 + AT_SHMV, pa0, pa1, pa2, pa3); at_partialSM(pA0, pA1, m_reg, alA, false);
;       __syncthreads(); SWAIT(); SWRITE(1, 1);
;       RESC(alA); __syncthreads();
.Lat_rare2_back:
	v_add_f32_e32 v173, v173, v175
	v_cvt_pk_bf16_f32 v104, v32, v33
	v_cvt_pk_bf16_f32 v105, v34, v35
	v_cvt_pk_bf16_f32 v106, v36, v37
	v_cvt_pk_bf16_f32 v107, v38, v39
	v_cvt_pk_bf16_f32 v108, v40, v41
	v_cvt_pk_bf16_f32 v109, v42, v43
	v_cvt_pk_bf16_f32 v110, v44, v45
	v_cvt_pk_bf16_f32 v111, v46, v47
	v_cvt_pk_bf16_f32 v112, v48, v49
	v_cvt_pk_bf16_f32 v113, v50, v51
	v_cvt_pk_bf16_f32 v114, v52, v53
	v_cvt_pk_bf16_f32 v115, v54, v55
	v_cvt_pk_bf16_f32 v116, v56, v57
	v_cvt_pk_bf16_f32 v117, v58, v59
	v_cvt_pk_bf16_f32 v118, v60, v61
	v_cvt_pk_bf16_f32 v119, v62, v63
	ds_read_b128 v[184:187], v170 offset:0
	ds_read_b128 v[188:191], v170 offset:6656
	ds_read_b128 v[192:195], v170 offset:32
	ds_read_b128 v[196:199], v170 offset:6688
	s_barrier
	ds_read_b128 v[200:203], v170 offset:64
	ds_read_b128 v[204:207], v170 offset:6720
	s_waitcnt lgkmcnt(4)
	v_mfma_f32_32x32x16_bf16 v[32:47], v[184:187], v[80:83], v[64:79]
	v_mfma_f32_32x32x16_bf16 v[48:63], v[188:191], v[80:83], v[64:79]
	ds_read_b128 v[208:211], v170 offset:96
	ds_read_b128 v[212:215], v170 offset:6752
	s_waitcnt lgkmcnt(4)
	v_mfma_f32_32x32x16_bf16 v[32:47], v[192:195], v[84:87], v[32:47]
	v_mfma_f32_32x32x16_bf16 v[48:63], v[196:199], v[84:87], v[48:63]
	ds_read_b128 v[184:187], v170 offset:128
	ds_read_b128 v[188:191], v170 offset:6784
	s_waitcnt lgkmcnt(4)
	v_mfma_f32_32x32x16_bf16 v[32:47], v[200:203], v[88:91], v[32:47]
	v_mfma_f32_32x32x16_bf16 v[48:63], v[204:207], v[88:91], v[48:63]
	ds_read_b128 v[192:195], v170 offset:160
	ds_read_b128 v[196:199], v170 offset:6816
	s_waitcnt lgkmcnt(4)
	v_mfma_f32_32x32x16_bf16 v[32:47], v[208:211], v[92:95], v[32:47]
	v_mfma_f32_32x32x16_bf16 v[48:63], v[212:215], v[92:95], v[48:63]
	ds_read_b64_tr_b16 v[148:149], v171 offset:49152
	ds_read_b64_tr_b16 v[150:151], v171 offset:51200
	ds_read_b64_tr_b16 v[152:153], v171 offset:53248
	ds_read_b64_tr_b16 v[154:155], v171 offset:55296
	s_waitcnt lgkmcnt(6)
	v_mfma_f32_32x32x16_bf16 v[32:47], v[184:187], v[96:99], v[32:47]
	v_mfma_f32_32x32x16_bf16 v[48:63], v[188:191], v[96:99], v[48:63]
	ds_read_b64_tr_b16 v[156:157], v171 offset:57344
	ds_read_b64_tr_b16 v[158:159], v171 offset:59392
	ds_read_b64_tr_b16 v[216:217], v171 offset:61440
	ds_read_b64_tr_b16 v[218:219], v171 offset:63488
	s_waitcnt lgkmcnt(8)
	v_mfma_f32_32x32x16_bf16 v[32:47], v[192:195], v[100:103], v[32:47]
	v_mfma_f32_32x32x16_bf16 v[48:63], v[196:199], v[100:103], v[48:63]
	ds_read_b64_tr_b16 v[220:221], v171 offset:49664
	ds_read_b64_tr_b16 v[222:223], v171 offset:51712
	ds_read_b64_tr_b16 v[224:225], v171 offset:53760
	ds_read_b64_tr_b16 v[226:227], v171 offset:55808
	s_waitcnt lgkmcnt(10)
	v_mfma_f32_32x32x16_bf16 v[0:15], v[104:107], v[148:151], v[0:15]
	s_waitcnt lgkmcnt(8)
	v_mfma_f32_32x32x16_bf16 v[0:15], v[108:111], v[152:155], v[0:15]
	ds_read_b64_tr_b16 v[236:237], v171 offset:57856
	ds_read_b64_tr_b16 v[238:239], v171 offset:59904
	ds_read_b64_tr_b16 v[240:241], v171 offset:61952
	ds_read_b64_tr_b16 v[242:243], v171 offset:64000
	s_waitcnt lgkmcnt(10)
	v_mfma_f32_32x32x16_bf16 v[0:15], v[112:115], v[156:159], v[0:15]
	s_waitcnt lgkmcnt(8)
	v_mfma_f32_32x32x16_bf16 v[0:15], v[116:119], v[216:219], v[0:15]
	s_waitcnt lgkmcnt(6)
	v_mfma_f32_32x32x16_bf16 v[16:31], v[104:107], v[220:223], v[16:31]
	s_waitcnt lgkmcnt(4)
	v_mfma_f32_32x32x16_bf16 v[16:31], v[108:111], v[224:227], v[16:31]
	s_waitcnt lgkmcnt(2)
	v_mfma_f32_32x32x16_bf16 v[16:31], v[112:115], v[236:239], v[16:31]
	s_waitcnt lgkmcnt(0)
	v_mfma_f32_32x32x16_bf16 v[16:31], v[116:119], v[240:243], v[16:31]
	s_barrier
	s_waitcnt vmcnt(0)
	s_add_i32 m0, s41, 0x19c00
	s_cmp_lt_u32 s14, 5
	global_load_lds_dwordx4 v246, s[86:87]
	v_add_u32_e32 v246, v248, v246
	s_cbranch_scc0 .Lat_kd8
	s_add_i32 m0, s30, 0x19c00
	s_nop 0
	global_load_lds_dwordx4 v250, s[86:87]
.Lat_kd8:
	v_add_u32_e32 v250, v252, v250
	s_add_i32 m0, s40, 0x8000
	s_nop 0
	global_load_lds_dwordx4 v131, s[36:37]
	s_add_u32 s36, s36, 0x40000
	s_addc_u32 s37, s37, 0
	v_exp_f32_e32 v32, v32
	v_exp_f32_e32 v48, v48
	v_exp_f32_e32 v33, v33
	v_exp_f32_e32 v49, v49
	v_exp_f32_e32 v34, v34
	v_exp_f32_e32 v50, v50
	v_exp_f32_e32 v35, v35
	v_exp_f32_e32 v51, v51
	v_exp_f32_e32 v36, v36
	v_exp_f32_e32 v52, v52
	v_exp_f32_e32 v37, v37
	v_exp_f32_e32 v53, v53
	v_exp_f32_e32 v38, v38
	v_exp_f32_e32 v54, v54
	v_exp_f32_e32 v39, v39
	v_exp_f32_e32 v55, v55
	v_exp_f32_e32 v40, v40
	v_exp_f32_e32 v56, v56
	v_exp_f32_e32 v41, v41
	v_exp_f32_e32 v57, v57
	v_exp_f32_e32 v42, v42
	v_exp_f32_e32 v58, v58
	v_exp_f32_e32 v43, v43
	v_exp_f32_e32 v59, v59
	v_exp_f32_e32 v44, v44
	v_exp_f32_e32 v60, v60
	v_exp_f32_e32 v45, v45
	v_exp_f32_e32 v61, v61
	v_exp_f32_e32 v46, v46
	v_exp_f32_e32 v62, v62
	v_exp_f32_e32 v47, v47
	v_exp_f32_e32 v63, v63
	v_add_f32_e32 v175, v32, v33
	v_add_f32_e32 v174, v48, v49
	v_add_f32_e32 v175, v175, v34
	v_add_f32_e32 v174, v174, v50
	v_add_f32_e32 v175, v175, v35
	v_add_f32_e32 v174, v174, v51
	v_add_f32_e32 v175, v175, v36
	v_add_f32_e32 v174, v174, v52
	v_add_f32_e32 v175, v175, v37
	v_add_f32_e32 v174, v174, v53
	v_add_f32_e32 v175, v175, v38
	v_add_f32_e32 v174, v174, v54
	v_add_f32_e32 v175, v175, v39
	v_add_f32_e32 v174, v174, v55
	v_add_f32_e32 v175, v175, v40
	v_add_f32_e32 v174, v174, v56
	v_add_f32_e32 v175, v175, v41
	v_add_f32_e32 v174, v174, v57
	v_add_f32_e32 v175, v175, v42
	v_add_f32_e32 v174, v174, v58
	v_add_f32_e32 v175, v175, v43
	v_add_f32_e32 v174, v174, v59
	v_add_f32_e32 v175, v175, v44
	v_add_f32_e32 v174, v174, v60
	v_add_f32_e32 v175, v175, v45
	v_add_f32_e32 v174, v174, v61
	v_add_f32_e32 v175, v175, v46
	v_add_f32_e32 v174, v174, v62
	v_add_f32_e32 v175, v175, v47
	v_add_f32_e32 v174, v174, v63
	v_add_f32_e32 v175, v175, v174
	v_cmp_ge_f32_e32 vcc, s23, v175
	s_cmp_eq_u64 vcc, exec
	s_cbranch_scc0 .Lat_rare3
